# sparse attention: the lagging waves (4-7) run one priority level above the leading waves in every segment
# speedup vs baseline: 1.0027x; 1.0027x over previous
.LBB0_56:
	v_pk_add_f32 v[66:67], v[66:67], v[98:99] op_sel:[0,1] op_sel_hi:[1,1] neg_lo:[0,1] neg_hi:[0,1]
	v_pk_add_f32 v[82:83], v[82:83], v[98:99] op_sel:[0,1] op_sel_hi:[1,1] neg_lo:[0,1] neg_hi:[0,1]
	v_exp_f32_e32 v66, v66
	v_exp_f32_e32 v67, v67
	v_exp_f32_e32 v82, v82
	v_exp_f32_e32 v83, v83
	v_pk_add_f32 v[68:69], v[68:69], v[98:99] op_sel:[0,1] op_sel_hi:[1,1] neg_lo:[0,1] neg_hi:[0,1]
	v_pk_add_f32 v[84:85], v[84:85], v[98:99] op_sel:[0,1] op_sel_hi:[1,1] neg_lo:[0,1] neg_hi:[0,1]
	v_exp_f32_e32 v68, v68
	v_exp_f32_e32 v69, v69
	v_exp_f32_e32 v84, v84
	v_exp_f32_e32 v85, v85
	v_pk_add_f32 v[100:101], v[66:67], v[82:83]
	v_pk_add_f32 v[70:71], v[70:71], v[98:99] op_sel:[0,1] op_sel_hi:[1,1] neg_lo:[0,1] neg_hi:[0,1]
	v_pk_add_f32 v[86:87], v[86:87], v[98:99] op_sel:[0,1] op_sel_hi:[1,1] neg_lo:[0,1] neg_hi:[0,1]
	v_exp_f32_e32 v70, v70
	v_exp_f32_e32 v71, v71
	v_exp_f32_e32 v86, v86
	v_exp_f32_e32 v87, v87
	v_pk_add_f32 v[100:101], v[100:101], v[68:69]
	v_pk_add_f32 v[100:101], v[100:101], v[84:85]
	v_pk_add_f32 v[72:73], v[72:73], v[98:99] op_sel:[0,1] op_sel_hi:[1,1] neg_lo:[0,1] neg_hi:[0,1]
	v_pk_add_f32 v[88:89], v[88:89], v[98:99] op_sel:[0,1] op_sel_hi:[1,1] neg_lo:[0,1] neg_hi:[0,1]
	v_exp_f32_e32 v72, v72
	v_exp_f32_e32 v73, v73
	v_exp_f32_e32 v88, v88
	v_exp_f32_e32 v89, v89
	v_pk_add_f32 v[100:101], v[100:101], v[70:71]
	v_pk_add_f32 v[100:101], v[100:101], v[86:87]
	v_pk_add_f32 v[74:75], v[74:75], v[98:99] op_sel:[0,1] op_sel_hi:[1,1] neg_lo:[0,1] neg_hi:[0,1]
	v_pk_add_f32 v[90:91], v[90:91], v[98:99] op_sel:[0,1] op_sel_hi:[1,1] neg_lo:[0,1] neg_hi:[0,1]
	v_exp_f32_e32 v74, v74
	v_exp_f32_e32 v75, v75
	v_exp_f32_e32 v90, v90
	v_exp_f32_e32 v91, v91
	v_pk_add_f32 v[100:101], v[100:101], v[72:73]
	v_pk_add_f32 v[100:101], v[100:101], v[88:89]
	v_pk_add_f32 v[76:77], v[76:77], v[98:99] op_sel:[0,1] op_sel_hi:[1,1] neg_lo:[0,1] neg_hi:[0,1]
	v_pk_add_f32 v[92:93], v[92:93], v[98:99] op_sel:[0,1] op_sel_hi:[1,1] neg_lo:[0,1] neg_hi:[0,1]
	v_exp_f32_e32 v76, v76
	v_exp_f32_e32 v77, v77
	v_exp_f32_e32 v92, v92
	v_exp_f32_e32 v93, v93
	v_pk_add_f32 v[100:101], v[100:101], v[74:75]
	v_pk_add_f32 v[100:101], v[100:101], v[90:91]
	v_pk_add_f32 v[78:79], v[78:79], v[98:99] op_sel:[0,1] op_sel_hi:[1,1] neg_lo:[0,1] neg_hi:[0,1]
	v_pk_add_f32 v[94:95], v[94:95], v[98:99] op_sel:[0,1] op_sel_hi:[1,1] neg_lo:[0,1] neg_hi:[0,1]
	v_exp_f32_e32 v78, v78
	v_exp_f32_e32 v79, v79
	v_exp_f32_e32 v94, v94
	v_exp_f32_e32 v95, v95
	v_pk_add_f32 v[100:101], v[100:101], v[76:77]
	v_pk_add_f32 v[100:101], v[100:101], v[92:93]
	v_pk_add_f32 v[80:81], v[80:81], v[98:99] op_sel:[0,1] op_sel_hi:[1,1] neg_lo:[0,1] neg_hi:[0,1]
	v_pk_add_f32 v[96:97], v[96:97], v[98:99] op_sel:[0,1] op_sel_hi:[1,1] neg_lo:[0,1] neg_hi:[0,1]
	v_exp_f32_e32 v80, v80
	v_exp_f32_e32 v81, v81
	v_exp_f32_e32 v96, v96
	v_exp_f32_e32 v97, v97
	v_pk_add_f32 v[100:101], v[100:101], v[78:79]
	v_pk_add_f32 v[100:101], v[100:101], v[94:95]
	s_nop 0
	v_pk_add_f32 v[100:101], v[100:101], v[80:81]
	v_pk_add_f32 v[100:101], v[100:101], v[96:97]
	v_add_f32_e32 v99, v100, v101
	s_mul_i32 s8, s48, 0x8c00
	v_fmac_f32_e32 v99, v193, v98
	v_add_u32_e32 v98, s8, v212
	v_cvt_pk_bf16_f32 v66, v66, v67
	v_cvt_pk_bf16_f32 v67, v68, v69
	v_cvt_pk_bf16_f32 v68, v70, v71
	v_cvt_pk_bf16_f32 v69, v72, v73
	v_cvt_pk_bf16_f32 v70, v74, v75
	v_cvt_pk_bf16_f32 v71, v76, v77
	v_cvt_pk_bf16_f32 v72, v78, v79
	v_cvt_pk_bf16_f32 v73, v80, v81
	v_cvt_pk_bf16_f32 v74, v82, v83
	v_cvt_pk_bf16_f32 v75, v84, v85
	v_cvt_pk_bf16_f32 v76, v86, v87
	v_cvt_pk_bf16_f32 v77, v88, v89
	v_cvt_pk_bf16_f32 v78, v90, v91
	v_cvt_pk_bf16_f32 v79, v92, v93
	v_cvt_pk_bf16_f32 v80, v94, v95
	v_cvt_pk_bf16_f32 v81, v96, v97
	ds_read_b128 v[82:85], v98 offset:17408
	ds_read_b128 v[86:89], v98 offset:22016
	ds_read_b128 v[90:93], v98 offset:26624
	ds_read_b128 v[94:97], v98 offset:31232
	s_setprio 2
	s_waitcnt lgkmcnt(3)
	v_mfma_f32_32x32x16_bf16 v[50:65], v[82:85], v[66:69], v[50:65]
	s_waitcnt lgkmcnt(2)
	v_mfma_f32_32x32x16_bf16 v[34:49], v[86:89], v[66:69], v[34:49]
	s_waitcnt lgkmcnt(1)
	v_mfma_f32_32x32x16_bf16 v[18:33], v[90:93], v[66:69], v[18:33]
	s_waitcnt lgkmcnt(0)
	v_mfma_f32_32x32x16_bf16 v[2:17], v[94:97], v[66:69], v[2:17]
	s_setprio 1
	ds_read_b128 v[66:69], v98 offset:17440
	ds_read_b128 v[82:85], v98 offset:22048
	ds_read_b128 v[86:89], v98 offset:26656
	ds_read_b128 v[90:93], v98 offset:31264
	s_setprio 2
	s_waitcnt lgkmcnt(3)
	v_mfma_f32_32x32x16_bf16 v[50:65], v[66:69], v[70:73], v[50:65]
	s_waitcnt lgkmcnt(2)
	v_mfma_f32_32x32x16_bf16 v[34:49], v[82:85], v[70:73], v[34:49]
	s_waitcnt lgkmcnt(1)
	v_mfma_f32_32x32x16_bf16 v[18:33], v[86:89], v[70:73], v[18:33]
	s_waitcnt lgkmcnt(0)
	v_mfma_f32_32x32x16_bf16 v[2:17], v[90:93], v[70:73], v[2:17]
	s_setprio 1
	ds_read_b128 v[66:69], v98 offset:17472
	ds_read_b128 v[70:73], v98 offset:22080
	ds_read_b128 v[82:85], v98 offset:26688
	ds_read_b128 v[86:89], v98 offset:31296
	s_setprio 2
	s_waitcnt lgkmcnt(3)
	v_mfma_f32_32x32x16_bf16 v[50:65], v[66:69], v[74:77], v[50:65]
	s_waitcnt lgkmcnt(2)
	v_mfma_f32_32x32x16_bf16 v[34:49], v[70:73], v[74:77], v[34:49]
	s_waitcnt lgkmcnt(1)
	v_mfma_f32_32x32x16_bf16 v[18:33], v[82:85], v[74:77], v[18:33]
	s_waitcnt lgkmcnt(0)
	v_mfma_f32_32x32x16_bf16 v[2:17], v[86:89], v[74:77], v[2:17]
	s_setprio 1
	ds_read_b128 v[66:69], v98 offset:17504
	ds_read_b128 v[70:73], v98 offset:22112
	ds_read_b128 v[74:77], v98 offset:26720
	ds_read_b128 v[82:85], v98 offset:31328
	s_setprio 2
	s_waitcnt lgkmcnt(3)
	v_mfma_f32_32x32x16_bf16 v[50:65], v[66:69], v[78:81], v[50:65]
	s_waitcnt lgkmcnt(2)
	v_mfma_f32_32x32x16_bf16 v[34:49], v[70:73], v[78:81], v[34:49]
	s_waitcnt lgkmcnt(1)
	v_mfma_f32_32x32x16_bf16 v[18:33], v[74:77], v[78:81], v[18:33]
	s_waitcnt lgkmcnt(0)
	v_mfma_f32_32x32x16_bf16 v[2:17], v[82:85], v[78:81], v[2:17]
	s_setprio 1
	v_mov_b32_e32 v193, v99

.LBB0_71:
	s_andn2_saveexec_b64 s[0:1], s[0:1]
	s_cbranch_execz .LBB0_78
	s_setprio 1
	s_cmp_eq_u32 s44, 3
	s_cbranch_scc1 .LBB0_76
	v_max3_f32 v174, v231, v66, v82
	s_nop 0
	v_max3_f32 v174, v174, v67, v83
	s_nop 0
	v_max3_f32 v174, v174, v68, v84
	s_nop 0
	v_max3_f32 v174, v174, v69, v85
	s_nop 0
	v_max3_f32 v174, v174, v70, v86
	s_nop 0
	v_max3_f32 v174, v174, v71, v87
	s_nop 0
	v_max3_f32 v174, v174, v72, v88
	s_nop 0
	v_max3_f32 v174, v174, v73, v89
	s_nop 0
	v_max3_f32 v174, v174, v74, v90
	s_nop 0
	v_max3_f32 v174, v174, v75, v91
	s_nop 0
	v_max3_f32 v174, v174, v76, v92
	s_nop 0
	v_max3_f32 v174, v174, v77, v93
	s_nop 0
	v_max3_f32 v174, v174, v78, v94
	s_nop 0
	v_max3_f32 v174, v174, v79, v95
	s_nop 0
	v_max3_f32 v174, v174, v80, v96
	s_nop 0
	v_max3_f32 v174, v174, v81, v97
	s_nop 0
	v_mov_b32_e32 v175, v174
	s_nop 1
	v_permlane32_swap_b32_e32 v174, v175
	v_max_f32_e32 v174, v174, v175
	v_add_f32_e32 v175, 0x41000000, v195
	v_cmp_gt_f32_e32 vcc, v174, v175
	v_max_f32_e32 v174, v195, v174
	s_nop 0
	v_cndmask_b32_e32 v215, v195, v174, vcc
	v_cmp_neq_f32_e32 vcc, s59, v215
	s_nop 1
	v_cndmask_b32_e32 v216, 0, v215, vcc
	v_sub_f32_e32 v174, v195, v216
	v_exp_f32_e32 v202, v174
	s_nop 0
	v_cmp_eq_f32_e32 vcc, 1.0, v202
	s_cmp_eq_u64 vcc, exec
	s_cbranch_scc1 .LBB0_75
	v_pk_mul_f32 v[64:65], v[64:65], v[202:203] op_sel_hi:[1,0]
	v_pk_mul_f32 v[62:63], v[62:63], v[202:203] op_sel_hi:[1,0]
	v_pk_mul_f32 v[60:61], v[60:61], v[202:203] op_sel_hi:[1,0]
	v_pk_mul_f32 v[58:59], v[58:59], v[202:203] op_sel_hi:[1,0]
	v_pk_mul_f32 v[56:57], v[56:57], v[202:203] op_sel_hi:[1,0]
	v_pk_mul_f32 v[54:55], v[54:55], v[202:203] op_sel_hi:[1,0]
	v_pk_mul_f32 v[52:53], v[52:53], v[202:203] op_sel_hi:[1,0]
	v_pk_mul_f32 v[50:51], v[50:51], v[202:203] op_sel_hi:[1,0]
	v_pk_mul_f32 v[48:49], v[48:49], v[202:203] op_sel_hi:[1,0]
	v_pk_mul_f32 v[46:47], v[46:47], v[202:203] op_sel_hi:[1,0]
	v_pk_mul_f32 v[44:45], v[44:45], v[202:203] op_sel_hi:[1,0]
	v_pk_mul_f32 v[42:43], v[42:43], v[202:203] op_sel_hi:[1,0]
	v_pk_mul_f32 v[40:41], v[40:41], v[202:203] op_sel_hi:[1,0]
	v_pk_mul_f32 v[38:39], v[38:39], v[202:203] op_sel_hi:[1,0]
	v_pk_mul_f32 v[36:37], v[36:37], v[202:203] op_sel_hi:[1,0]
	v_pk_mul_f32 v[34:35], v[34:35], v[202:203] op_sel_hi:[1,0]
	v_pk_mul_f32 v[32:33], v[32:33], v[202:203] op_sel_hi:[1,0]
	v_pk_mul_f32 v[30:31], v[30:31], v[202:203] op_sel_hi:[1,0]
	v_pk_mul_f32 v[28:29], v[28:29], v[202:203] op_sel_hi:[1,0]
	v_pk_mul_f32 v[26:27], v[26:27], v[202:203] op_sel_hi:[1,0]
	v_pk_mul_f32 v[24:25], v[24:25], v[202:203] op_sel_hi:[1,0]
	v_pk_mul_f32 v[22:23], v[22:23], v[202:203] op_sel_hi:[1,0]
	v_pk_mul_f32 v[20:21], v[20:21], v[202:203] op_sel_hi:[1,0]
	v_pk_mul_f32 v[18:19], v[18:19], v[202:203] op_sel_hi:[1,0]
	v_pk_mul_f32 v[16:17], v[16:17], v[202:203] op_sel_hi:[1,0]
	v_pk_mul_f32 v[14:15], v[14:15], v[202:203] op_sel_hi:[1,0]
	v_pk_mul_f32 v[12:13], v[12:13], v[202:203] op_sel_hi:[1,0]
	v_pk_mul_f32 v[10:11], v[10:11], v[202:203] op_sel_hi:[1,0]
	v_pk_mul_f32 v[8:9], v[8:9], v[202:203] op_sel_hi:[1,0]
	v_pk_mul_f32 v[6:7], v[6:7], v[202:203] op_sel_hi:[1,0]
	v_pk_mul_f32 v[4:5], v[4:5], v[202:203] op_sel_hi:[1,0]
	v_pk_mul_f32 v[2:3], v[2:3], v[202:203] op_sel_hi:[1,0]
.LBB0_75:
	v_pk_add_f32 v[66:67], v[66:67], v[216:217] op_sel_hi:[1,0] neg_lo:[0,1] neg_hi:[0,1]
	v_pk_add_f32 v[82:83], v[82:83], v[216:217] op_sel_hi:[1,0] neg_lo:[0,1] neg_hi:[0,1]
	v_exp_f32_e32 v66, v66
	v_exp_f32_e32 v67, v67
	v_exp_f32_e32 v82, v82
	v_exp_f32_e32 v83, v83
	v_pk_add_f32 v[68:69], v[68:69], v[216:217] op_sel_hi:[1,0] neg_lo:[0,1] neg_hi:[0,1]
	v_pk_add_f32 v[84:85], v[84:85], v[216:217] op_sel_hi:[1,0] neg_lo:[0,1] neg_hi:[0,1]
	v_exp_f32_e32 v68, v68
	v_exp_f32_e32 v69, v69
	v_exp_f32_e32 v84, v84
	v_exp_f32_e32 v85, v85
	v_pk_add_f32 v[174:175], v[66:67], v[82:83]
	v_pk_add_f32 v[70:71], v[70:71], v[216:217] op_sel_hi:[1,0] neg_lo:[0,1] neg_hi:[0,1]
	v_pk_add_f32 v[86:87], v[86:87], v[216:217] op_sel_hi:[1,0] neg_lo:[0,1] neg_hi:[0,1]
	v_exp_f32_e32 v70, v70
	v_exp_f32_e32 v71, v71
	v_exp_f32_e32 v86, v86
	v_exp_f32_e32 v87, v87
	v_pk_add_f32 v[174:175], v[174:175], v[68:69]
	v_pk_add_f32 v[174:175], v[174:175], v[84:85]
	v_pk_add_f32 v[72:73], v[72:73], v[216:217] op_sel_hi:[1,0] neg_lo:[0,1] neg_hi:[0,1]
	v_pk_add_f32 v[88:89], v[88:89], v[216:217] op_sel_hi:[1,0] neg_lo:[0,1] neg_hi:[0,1]
	v_exp_f32_e32 v72, v72
	v_exp_f32_e32 v73, v73
	v_exp_f32_e32 v88, v88
	v_exp_f32_e32 v89, v89
	v_pk_add_f32 v[174:175], v[174:175], v[70:71]
	v_pk_add_f32 v[174:175], v[174:175], v[86:87]
	v_pk_add_f32 v[74:75], v[74:75], v[216:217] op_sel_hi:[1,0] neg_lo:[0,1] neg_hi:[0,1]
	v_pk_add_f32 v[90:91], v[90:91], v[216:217] op_sel_hi:[1,0] neg_lo:[0,1] neg_hi:[0,1]
	v_exp_f32_e32 v74, v74
	v_exp_f32_e32 v75, v75
	v_exp_f32_e32 v90, v90
	v_exp_f32_e32 v91, v91
	v_pk_add_f32 v[174:175], v[174:175], v[72:73]
	v_pk_add_f32 v[174:175], v[174:175], v[88:89]
	v_pk_add_f32 v[76:77], v[76:77], v[216:217] op_sel_hi:[1,0] neg_lo:[0,1] neg_hi:[0,1]
	v_pk_add_f32 v[92:93], v[92:93], v[216:217] op_sel_hi:[1,0] neg_lo:[0,1] neg_hi:[0,1]
	v_exp_f32_e32 v76, v76
	v_exp_f32_e32 v77, v77
	v_exp_f32_e32 v92, v92
	v_exp_f32_e32 v93, v93
	v_pk_add_f32 v[174:175], v[174:175], v[74:75]
	v_pk_add_f32 v[174:175], v[174:175], v[90:91]
	v_pk_add_f32 v[78:79], v[78:79], v[216:217] op_sel_hi:[1,0] neg_lo:[0,1] neg_hi:[0,1]
	v_pk_add_f32 v[94:95], v[94:95], v[216:217] op_sel_hi:[1,0] neg_lo:[0,1] neg_hi:[0,1]
	v_exp_f32_e32 v78, v78
	v_exp_f32_e32 v79, v79
	v_exp_f32_e32 v94, v94
	v_exp_f32_e32 v95, v95
	v_pk_add_f32 v[174:175], v[174:175], v[76:77]
	v_pk_add_f32 v[174:175], v[174:175], v[92:93]
	v_pk_add_f32 v[80:81], v[80:81], v[216:217] op_sel_hi:[1,0] neg_lo:[0,1] neg_hi:[0,1]
	v_pk_add_f32 v[96:97], v[96:97], v[216:217] op_sel_hi:[1,0] neg_lo:[0,1] neg_hi:[0,1]
	v_exp_f32_e32 v80, v80
	v_exp_f32_e32 v81, v81
	v_exp_f32_e32 v96, v96
	v_exp_f32_e32 v97, v97
	v_pk_add_f32 v[174:175], v[174:175], v[78:79]
	v_pk_add_f32 v[174:175], v[174:175], v[94:95]
	s_mul_i32 s48, s48, 0x8c00
	s_nop 0
	v_pk_add_f32 v[174:175], v[174:175], v[80:81]
	v_pk_add_f32 v[174:175], v[174:175], v[96:97]
	v_add_f32_e32 v216, v174, v175
	v_add_u32_e32 v174, s48, v212
	v_cvt_pk_bf16_f32 v66, v66, v67
	v_cvt_pk_bf16_f32 v67, v68, v69
	v_cvt_pk_bf16_f32 v68, v70, v71
	v_cvt_pk_bf16_f32 v69, v72, v73
	v_cvt_pk_bf16_f32 v70, v74, v75
	v_cvt_pk_bf16_f32 v71, v76, v77
	v_cvt_pk_bf16_f32 v72, v78, v79
	v_cvt_pk_bf16_f32 v73, v80, v81
	v_cvt_pk_bf16_f32 v74, v82, v83
	v_cvt_pk_bf16_f32 v75, v84, v85
	v_cvt_pk_bf16_f32 v76, v86, v87
	v_cvt_pk_bf16_f32 v77, v88, v89
	v_cvt_pk_bf16_f32 v78, v90, v91
	v_cvt_pk_bf16_f32 v79, v92, v93
	v_cvt_pk_bf16_f32 v80, v94, v95
	v_cvt_pk_bf16_f32 v81, v96, v97
	ds_read_b128 v[82:85], v174 offset:17408
	ds_read_b128 v[86:89], v174 offset:22016
	ds_read_b128 v[90:93], v174 offset:26624
	ds_read_b128 v[94:97], v174 offset:31232
	v_fmac_f32_e32 v216, v193, v202
	s_setprio 2
	s_waitcnt lgkmcnt(3)
	v_mfma_f32_32x32x16_bf16 v[50:65], v[82:85], v[66:69], v[50:65]
	s_waitcnt lgkmcnt(2)
	v_mfma_f32_32x32x16_bf16 v[34:49], v[86:89], v[66:69], v[34:49]
	s_waitcnt lgkmcnt(1)
	v_mfma_f32_32x32x16_bf16 v[18:33], v[90:93], v[66:69], v[18:33]
	s_waitcnt lgkmcnt(0)
	v_mfma_f32_32x32x16_bf16 v[2:17], v[94:97], v[66:69], v[2:17]
	s_setprio 1
	ds_read_b128 v[66:69], v174 offset:17440
	ds_read_b128 v[82:85], v174 offset:22048
	ds_read_b128 v[86:89], v174 offset:26656
	ds_read_b128 v[90:93], v174 offset:31264
	s_setprio 2
	s_waitcnt lgkmcnt(3)
	v_mfma_f32_32x32x16_bf16 v[50:65], v[66:69], v[70:73], v[50:65]
	s_waitcnt lgkmcnt(2)
	v_mfma_f32_32x32x16_bf16 v[34:49], v[82:85], v[70:73], v[34:49]
	s_waitcnt lgkmcnt(1)
	v_mfma_f32_32x32x16_bf16 v[18:33], v[86:89], v[70:73], v[18:33]
	s_waitcnt lgkmcnt(0)
	v_mfma_f32_32x32x16_bf16 v[2:17], v[90:93], v[70:73], v[2:17]
	s_setprio 1
	ds_read_b128 v[66:69], v174 offset:17472
	ds_read_b128 v[70:73], v174 offset:22080
	ds_read_b128 v[82:85], v174 offset:26688
	ds_read_b128 v[86:89], v174 offset:31296
	s_setprio 2
	s_waitcnt lgkmcnt(3)
	v_mfma_f32_32x32x16_bf16 v[50:65], v[66:69], v[74:77], v[50:65]
	s_waitcnt lgkmcnt(2)
	v_mfma_f32_32x32x16_bf16 v[34:49], v[70:73], v[74:77], v[34:49]
	s_waitcnt lgkmcnt(1)
	v_mfma_f32_32x32x16_bf16 v[18:33], v[82:85], v[74:77], v[18:33]
	s_waitcnt lgkmcnt(0)
	v_mfma_f32_32x32x16_bf16 v[2:17], v[86:89], v[74:77], v[2:17]
	s_setprio 1
	ds_read_b128 v[66:69], v174 offset:17504
	ds_read_b128 v[70:73], v174 offset:22112
	ds_read_b128 v[74:77], v174 offset:26720
	ds_read_b128 v[82:85], v174 offset:31328
	s_setprio 2
	s_waitcnt lgkmcnt(3)
	v_mfma_f32_32x32x16_bf16 v[50:65], v[66:69], v[78:81], v[50:65]
	s_waitcnt lgkmcnt(2)
	v_mfma_f32_32x32x16_bf16 v[34:49], v[70:73], v[78:81], v[34:49]
	s_waitcnt lgkmcnt(1)
	v_mfma_f32_32x32x16_bf16 v[18:33], v[74:77], v[78:81], v[18:33]
	s_waitcnt lgkmcnt(0)
	v_mfma_f32_32x32x16_bf16 v[2:17], v[82:85], v[78:81], v[2:17]
	s_setprio 1
	s_branch .LBB0_77

.LBB0_77:
	v_not_b32_e32 v66, v218
	v_not_b32_e32 v82, v203
	v_bfe_i32 v83, v66, 0, 1
	v_bfe_i32 v174, v82, 0, 1
	v_bfe_i32 v67, v66, 1, 1
	v_bfe_i32 v175, v82, 1, 1
	v_bfe_i32 v68, v66, 2, 1
	v_bfe_i32 v84, v82, 2, 1
	v_bfe_i32 v69, v66, 3, 1
	v_bfe_i32 v85, v82, 3, 1
	v_bfe_i32 v70, v66, 8, 1
	v_bfe_i32 v86, v82, 8, 1
	v_bfe_i32 v71, v66, 9, 1
	v_bfe_i32 v87, v82, 9, 1
	v_bfe_i32 v72, v66, 10, 1
	v_bfe_i32 v88, v82, 10, 1
	v_bfe_i32 v73, v66, 11, 1
	v_bfe_i32 v89, v82, 11, 1
	v_bfe_i32 v74, v66, 16, 1
	v_bfe_i32 v90, v82, 16, 1
	v_bfe_i32 v75, v66, 17, 1
	v_bfe_i32 v91, v82, 17, 1
	v_bfe_i32 v76, v66, 18, 1
	v_bfe_i32 v92, v82, 18, 1
	v_bfe_i32 v77, v66, 19, 1
	v_bfe_i32 v93, v82, 19, 1
	v_bfe_i32 v78, v66, 24, 1
	v_bfe_i32 v94, v82, 24, 1
	v_bfe_i32 v79, v66, 25, 1
	v_bfe_i32 v95, v82, 25, 1
	v_bfe_i32 v80, v66, 26, 1
	v_bfe_i32 v96, v82, 26, 1
	v_bfe_i32 v66, v66, 27, 1
	v_bfe_i32 v82, v82, 27, 1
	s_nop 0
	v_and_b32_e32 v79, 0xff800000, v79
	v_and_b32_e32 v81, 0xff800000, v66
	v_and_b32_e32 v66, 0xff800000, v83
	v_and_b32_e32 v97, 0xff800000, v82
	v_and_b32_e32 v83, 0xff800000, v175
	v_and_b32_e32 v82, 0xff800000, v174
	ds_read_b128 v[174:177], v217 offset:8704
	ds_read_b128 v[218:221], v217
	ds_read_b128 v[222:225], v217 offset:32
	ds_read_b128 v[226:229], v217 offset:8736
	ds_read_b128 v[232:235], v217 offset:64
	ds_read_b128 v[236:239], v217 offset:8768
	ds_read_b128 v[240:243], v217 offset:96
	ds_read_b128 v[248:251], v217 offset:8800
	v_and_b32_e32 v80, 0xff800000, v80
	v_and_b32_e32 v78, 0xff800000, v78
	v_and_b32_e32 v77, 0xff800000, v77
	v_and_b32_e32 v76, 0xff800000, v76
	v_and_b32_e32 v75, 0xff800000, v75
	v_and_b32_e32 v74, 0xff800000, v74
	v_and_b32_e32 v73, 0xff800000, v73
	v_and_b32_e32 v72, 0xff800000, v72
	v_and_b32_e32 v71, 0xff800000, v71
	v_and_b32_e32 v70, 0xff800000, v70
	v_and_b32_e32 v69, 0xff800000, v69
	v_and_b32_e32 v68, 0xff800000, v68
	v_and_b32_e32 v67, 0xff800000, v67
	v_and_b32_e32 v96, 0xff800000, v96
	v_and_b32_e32 v95, 0xff800000, v95
	v_and_b32_e32 v94, 0xff800000, v94
	v_and_b32_e32 v93, 0xff800000, v93
	v_and_b32_e32 v92, 0xff800000, v92
	v_and_b32_e32 v91, 0xff800000, v91
	v_and_b32_e32 v90, 0xff800000, v90
	v_and_b32_e32 v89, 0xff800000, v89
	v_and_b32_e32 v88, 0xff800000, v88
	v_and_b32_e32 v87, 0xff800000, v87
	v_and_b32_e32 v86, 0xff800000, v86
	v_and_b32_e32 v85, 0xff800000, v85
	v_and_b32_e32 v84, 0xff800000, v84
	s_setprio 2
	s_waitcnt lgkmcnt(6)
	v_mfma_f32_32x32x16_bf16 v[66:81], v[218:221], v[98:101], v[66:81]
	v_mfma_f32_32x32x16_bf16 v[82:97], v[174:177], v[98:101], v[82:97]
	s_waitcnt lgkmcnt(5)
	v_mfma_f32_32x32x16_bf16 v[66:81], v[222:225], v[102:105], v[66:81]
	s_waitcnt lgkmcnt(4)
	v_mfma_f32_32x32x16_bf16 v[82:97], v[226:229], v[102:105], v[82:97]
	s_waitcnt lgkmcnt(3)
	v_mfma_f32_32x32x16_bf16 v[66:81], v[232:235], v[106:109], v[66:81]
	s_waitcnt lgkmcnt(2)
	v_mfma_f32_32x32x16_bf16 v[82:97], v[236:239], v[106:109], v[82:97]
	s_waitcnt lgkmcnt(1)
	v_mfma_f32_32x32x16_bf16 v[66:81], v[240:243], v[110:113], v[66:81]
	s_waitcnt lgkmcnt(0)
	v_mfma_f32_32x32x16_bf16 v[82:97], v[248:251], v[110:113], v[82:97]
	s_setprio 1
	ds_read_b128 v[174:177], v217 offset:128
	ds_read_b128 v[218:221], v217 offset:160
	ds_read_b128 v[222:225], v217 offset:8832
	ds_read_b128 v[226:229], v217 offset:8864
	ds_read_b128 v[232:235], v217 offset:192
	ds_read_b128 v[236:239], v217 offset:224
	ds_read_b128 v[240:243], v217 offset:8896
	ds_read_b128 v[248:251], v217 offset:8928
	s_setprio 2
	s_waitcnt lgkmcnt(7)
	v_mfma_f32_32x32x16_bf16 v[66:81], v[174:177], v[114:117], v[66:81]
	s_waitcnt lgkmcnt(5)
	v_mfma_f32_32x32x16_bf16 v[82:97], v[222:225], v[114:117], v[82:97]
	v_mfma_f32_32x32x16_bf16 v[66:81], v[218:221], v[118:121], v[66:81]
	s_waitcnt lgkmcnt(4)
	v_mfma_f32_32x32x16_bf16 v[82:97], v[226:229], v[118:121], v[82:97]
	s_waitcnt lgkmcnt(3)
	v_mfma_f32_32x32x16_bf16 v[66:81], v[232:235], v[122:125], v[66:81]
	s_waitcnt lgkmcnt(1)
	v_mfma_f32_32x32x16_bf16 v[82:97], v[240:243], v[122:125], v[82:97]
	v_mfma_f32_32x32x16_bf16 v[66:81], v[236:239], v[126:129], v[66:81]
	s_waitcnt lgkmcnt(0)
	v_mfma_f32_32x32x16_bf16 v[82:97], v[248:251], v[126:129], v[82:97]
	s_setprio 1

.LBB0_93:
	s_setprio 1
	v_max3_f32 v174, v231, v66, v82
	s_nop 0
	v_max3_f32 v174, v174, v67, v83
	s_nop 0
	v_max3_f32 v174, v174, v68, v84
	s_nop 0
	v_max3_f32 v174, v174, v69, v85
	s_nop 0
	v_max3_f32 v174, v174, v70, v86
	s_nop 0
	v_max3_f32 v174, v174, v71, v87
	s_nop 0
	v_max3_f32 v174, v174, v72, v88
	s_nop 0
	v_max3_f32 v174, v174, v73, v89
	s_nop 0
	v_max3_f32 v174, v174, v74, v90
	s_nop 0
	v_max3_f32 v174, v174, v75, v91
	s_nop 0
	v_max3_f32 v174, v174, v76, v92
	s_nop 0
	v_max3_f32 v174, v174, v77, v93
	s_nop 0
	v_max3_f32 v174, v174, v78, v94
	s_nop 0
	v_max3_f32 v174, v174, v79, v95
	s_nop 0
	v_max3_f32 v174, v174, v80, v96
	s_nop 0
	v_max3_f32 v174, v174, v81, v97
	s_nop 0
	v_mov_b32_e32 v175, v174
	s_nop 1
	v_permlane32_swap_b32_e32 v174, v175
	v_max_f32_e32 v174, v174, v175
	v_add_f32_e32 v175, 0x41000000, v215
	v_cmp_gt_f32_e32 vcc, v174, v175
	v_max_f32_e32 v174, v215, v174
	s_nop 0
	v_cndmask_b32_e32 v195, v215, v174, vcc
	v_cmp_neq_f32_e32 vcc, s59, v195
	s_nop 1
	v_cndmask_b32_e32 v193, 0, v195, vcc
	v_sub_f32_e32 v174, v215, v193
	v_exp_f32_e32 v204, v174
	s_nop 0
	v_cmp_eq_f32_e32 vcc, 1.0, v204
	s_cmp_lg_u64 vcc, exec
	s_cbranch_scc0 .LBB0_95
	v_pk_mul_f32 v[64:65], v[64:65], v[204:205] op_sel_hi:[1,0]
	v_pk_mul_f32 v[62:63], v[62:63], v[204:205] op_sel_hi:[1,0]
	v_pk_mul_f32 v[60:61], v[60:61], v[204:205] op_sel_hi:[1,0]
	v_pk_mul_f32 v[58:59], v[58:59], v[204:205] op_sel_hi:[1,0]
	v_pk_mul_f32 v[56:57], v[56:57], v[204:205] op_sel_hi:[1,0]
	v_pk_mul_f32 v[54:55], v[54:55], v[204:205] op_sel_hi:[1,0]
	v_pk_mul_f32 v[52:53], v[52:53], v[204:205] op_sel_hi:[1,0]
	v_pk_mul_f32 v[50:51], v[50:51], v[204:205] op_sel_hi:[1,0]
	v_pk_mul_f32 v[48:49], v[48:49], v[204:205] op_sel_hi:[1,0]
	v_pk_mul_f32 v[46:47], v[46:47], v[204:205] op_sel_hi:[1,0]
	v_pk_mul_f32 v[44:45], v[44:45], v[204:205] op_sel_hi:[1,0]
	v_pk_mul_f32 v[42:43], v[42:43], v[204:205] op_sel_hi:[1,0]
	v_pk_mul_f32 v[40:41], v[40:41], v[204:205] op_sel_hi:[1,0]
	v_pk_mul_f32 v[38:39], v[38:39], v[204:205] op_sel_hi:[1,0]
	v_pk_mul_f32 v[36:37], v[36:37], v[204:205] op_sel_hi:[1,0]
	v_pk_mul_f32 v[34:35], v[34:35], v[204:205] op_sel_hi:[1,0]
	v_pk_mul_f32 v[32:33], v[32:33], v[204:205] op_sel_hi:[1,0]
	v_pk_mul_f32 v[30:31], v[30:31], v[204:205] op_sel_hi:[1,0]
	v_pk_mul_f32 v[28:29], v[28:29], v[204:205] op_sel_hi:[1,0]
	v_pk_mul_f32 v[26:27], v[26:27], v[204:205] op_sel_hi:[1,0]
	v_pk_mul_f32 v[24:25], v[24:25], v[204:205] op_sel_hi:[1,0]
	v_pk_mul_f32 v[22:23], v[22:23], v[204:205] op_sel_hi:[1,0]
	v_pk_mul_f32 v[20:21], v[20:21], v[204:205] op_sel_hi:[1,0]
	v_pk_mul_f32 v[18:19], v[18:19], v[204:205] op_sel_hi:[1,0]
	v_pk_mul_f32 v[16:17], v[16:17], v[204:205] op_sel_hi:[1,0]
	v_pk_mul_f32 v[14:15], v[14:15], v[204:205] op_sel_hi:[1,0]
	v_pk_mul_f32 v[12:13], v[12:13], v[204:205] op_sel_hi:[1,0]
	v_pk_mul_f32 v[10:11], v[10:11], v[204:205] op_sel_hi:[1,0]
	v_pk_mul_f32 v[8:9], v[8:9], v[204:205] op_sel_hi:[1,0]
	v_pk_mul_f32 v[6:7], v[6:7], v[204:205] op_sel_hi:[1,0]
	v_pk_mul_f32 v[4:5], v[4:5], v[204:205] op_sel_hi:[1,0]
	v_pk_mul_f32 v[2:3], v[2:3], v[204:205] op_sel_hi:[1,0]
.LBB0_95:
	v_pk_add_f32 v[66:67], v[66:67], v[192:193] op_sel:[0,1] op_sel_hi:[1,1] neg_lo:[0,1] neg_hi:[0,1]
	v_pk_add_f32 v[82:83], v[82:83], v[192:193] op_sel:[0,1] op_sel_hi:[1,1] neg_lo:[0,1] neg_hi:[0,1]
	v_exp_f32_e32 v66, v66
	v_exp_f32_e32 v67, v67
	v_exp_f32_e32 v82, v82
	v_exp_f32_e32 v83, v83
	v_pk_add_f32 v[68:69], v[68:69], v[192:193] op_sel:[0,1] op_sel_hi:[1,1] neg_lo:[0,1] neg_hi:[0,1]
	v_pk_add_f32 v[84:85], v[84:85], v[192:193] op_sel:[0,1] op_sel_hi:[1,1] neg_lo:[0,1] neg_hi:[0,1]
	v_exp_f32_e32 v68, v68
	v_exp_f32_e32 v69, v69
	v_exp_f32_e32 v84, v84
	v_exp_f32_e32 v85, v85
	v_pk_add_f32 v[174:175], v[66:67], v[82:83]
	v_pk_add_f32 v[70:71], v[70:71], v[192:193] op_sel:[0,1] op_sel_hi:[1,1] neg_lo:[0,1] neg_hi:[0,1]
	v_pk_add_f32 v[86:87], v[86:87], v[192:193] op_sel:[0,1] op_sel_hi:[1,1] neg_lo:[0,1] neg_hi:[0,1]
	v_exp_f32_e32 v70, v70
	v_exp_f32_e32 v71, v71
	v_exp_f32_e32 v86, v86
	v_exp_f32_e32 v87, v87
	v_pk_add_f32 v[174:175], v[174:175], v[68:69]
	v_pk_add_f32 v[174:175], v[174:175], v[84:85]
	v_pk_add_f32 v[72:73], v[72:73], v[192:193] op_sel:[0,1] op_sel_hi:[1,1] neg_lo:[0,1] neg_hi:[0,1]
	v_pk_add_f32 v[88:89], v[88:89], v[192:193] op_sel:[0,1] op_sel_hi:[1,1] neg_lo:[0,1] neg_hi:[0,1]
	v_exp_f32_e32 v72, v72
	v_exp_f32_e32 v73, v73
	v_exp_f32_e32 v88, v88
	v_exp_f32_e32 v89, v89
	v_pk_add_f32 v[174:175], v[174:175], v[70:71]
	v_pk_add_f32 v[174:175], v[174:175], v[86:87]
	v_pk_add_f32 v[74:75], v[74:75], v[192:193] op_sel:[0,1] op_sel_hi:[1,1] neg_lo:[0,1] neg_hi:[0,1]
	v_pk_add_f32 v[90:91], v[90:91], v[192:193] op_sel:[0,1] op_sel_hi:[1,1] neg_lo:[0,1] neg_hi:[0,1]
	v_exp_f32_e32 v74, v74
	v_exp_f32_e32 v75, v75
	v_exp_f32_e32 v90, v90
	v_exp_f32_e32 v91, v91
	v_pk_add_f32 v[174:175], v[174:175], v[72:73]
	v_pk_add_f32 v[174:175], v[174:175], v[88:89]
	v_pk_add_f32 v[76:77], v[76:77], v[192:193] op_sel:[0,1] op_sel_hi:[1,1] neg_lo:[0,1] neg_hi:[0,1]
	v_pk_add_f32 v[92:93], v[92:93], v[192:193] op_sel:[0,1] op_sel_hi:[1,1] neg_lo:[0,1] neg_hi:[0,1]
	v_exp_f32_e32 v76, v76
	v_exp_f32_e32 v77, v77
	v_exp_f32_e32 v92, v92
	v_exp_f32_e32 v93, v93
	v_pk_add_f32 v[174:175], v[174:175], v[74:75]
	v_pk_add_f32 v[174:175], v[174:175], v[90:91]
	v_pk_add_f32 v[78:79], v[78:79], v[192:193] op_sel:[0,1] op_sel_hi:[1,1] neg_lo:[0,1] neg_hi:[0,1]
	v_pk_add_f32 v[94:95], v[94:95], v[192:193] op_sel:[0,1] op_sel_hi:[1,1] neg_lo:[0,1] neg_hi:[0,1]
	v_exp_f32_e32 v78, v78
	v_exp_f32_e32 v79, v79
	v_exp_f32_e32 v94, v94
	v_exp_f32_e32 v95, v95
	v_pk_add_f32 v[174:175], v[174:175], v[76:77]
	v_pk_add_f32 v[174:175], v[174:175], v[92:93]
	v_pk_add_f32 v[80:81], v[80:81], v[192:193] op_sel:[0,1] op_sel_hi:[1,1] neg_lo:[0,1] neg_hi:[0,1]
	v_pk_add_f32 v[96:97], v[96:97], v[192:193] op_sel:[0,1] op_sel_hi:[1,1] neg_lo:[0,1] neg_hi:[0,1]
	v_exp_f32_e32 v80, v80
	v_exp_f32_e32 v81, v81
	v_exp_f32_e32 v96, v96
	v_exp_f32_e32 v97, v97
	v_pk_add_f32 v[174:175], v[174:175], v[78:79]
	v_pk_add_f32 v[174:175], v[174:175], v[94:95]
	s_nop 0
	v_pk_add_f32 v[174:175], v[174:175], v[80:81]
	v_pk_add_f32 v[174:175], v[174:175], v[96:97]
	v_add_f32_e32 v193, v174, v175
	v_add3_u32 v174, s47, v210, v211
	v_cvt_pk_bf16_f32 v66, v66, v67
	v_cvt_pk_bf16_f32 v67, v68, v69
	v_cvt_pk_bf16_f32 v68, v70, v71
	v_cvt_pk_bf16_f32 v69, v72, v73
	v_cvt_pk_bf16_f32 v70, v74, v75
	v_cvt_pk_bf16_f32 v71, v76, v77
	v_cvt_pk_bf16_f32 v72, v78, v79
	v_cvt_pk_bf16_f32 v73, v80, v81
	v_cvt_pk_bf16_f32 v74, v82, v83
	v_cvt_pk_bf16_f32 v75, v84, v85
	v_cvt_pk_bf16_f32 v76, v86, v87
	v_cvt_pk_bf16_f32 v77, v88, v89
	v_cvt_pk_bf16_f32 v78, v90, v91
	v_cvt_pk_bf16_f32 v79, v92, v93
	v_cvt_pk_bf16_f32 v80, v94, v95
	v_cvt_pk_bf16_f32 v81, v96, v97
	ds_read_b128 v[82:85], v174 offset:17408
	ds_read_b128 v[86:89], v174 offset:22016
	ds_read_b128 v[90:93], v174 offset:26624
	ds_read_b128 v[94:97], v174 offset:31232
	v_fmac_f32_e32 v193, v216, v204
	s_setprio 2
	s_waitcnt lgkmcnt(3)
	v_mfma_f32_32x32x16_bf16 v[50:65], v[82:85], v[66:69], v[50:65]
	s_waitcnt lgkmcnt(2)
	v_mfma_f32_32x32x16_bf16 v[34:49], v[86:89], v[66:69], v[34:49]
	s_waitcnt lgkmcnt(1)
	v_mfma_f32_32x32x16_bf16 v[18:33], v[90:93], v[66:69], v[18:33]
	s_waitcnt lgkmcnt(0)
	v_mfma_f32_32x32x16_bf16 v[2:17], v[94:97], v[66:69], v[2:17]
	s_setprio 1
	ds_read_b128 v[66:69], v174 offset:17440
	ds_read_b128 v[82:85], v174 offset:22048
	ds_read_b128 v[86:89], v174 offset:26656
	ds_read_b128 v[90:93], v174 offset:31264
	s_setprio 2
	s_waitcnt lgkmcnt(3)
	v_mfma_f32_32x32x16_bf16 v[50:65], v[66:69], v[70:73], v[50:65]
	s_waitcnt lgkmcnt(2)
	v_mfma_f32_32x32x16_bf16 v[34:49], v[82:85], v[70:73], v[34:49]
	s_waitcnt lgkmcnt(1)
	v_mfma_f32_32x32x16_bf16 v[18:33], v[86:89], v[70:73], v[18:33]
	s_waitcnt lgkmcnt(0)
	v_mfma_f32_32x32x16_bf16 v[2:17], v[90:93], v[70:73], v[2:17]
	s_setprio 1
	ds_read_b128 v[66:69], v174 offset:17472
	ds_read_b128 v[70:73], v174 offset:22080
	ds_read_b128 v[82:85], v174 offset:26688
	ds_read_b128 v[86:89], v174 offset:31296
	s_setprio 2
	s_waitcnt lgkmcnt(3)
	v_mfma_f32_32x32x16_bf16 v[50:65], v[66:69], v[74:77], v[50:65]
	s_waitcnt lgkmcnt(2)
	v_mfma_f32_32x32x16_bf16 v[34:49], v[70:73], v[74:77], v[34:49]
	s_waitcnt lgkmcnt(1)
	v_mfma_f32_32x32x16_bf16 v[18:33], v[82:85], v[74:77], v[18:33]
	s_waitcnt lgkmcnt(0)
	v_mfma_f32_32x32x16_bf16 v[2:17], v[86:89], v[74:77], v[2:17]
	s_setprio 1
	ds_read_b128 v[66:69], v174 offset:17504
	ds_read_b128 v[70:73], v174 offset:22112
	ds_read_b128 v[74:77], v174 offset:26720
	ds_read_b128 v[82:85], v174 offset:31328
	s_setprio 2
	s_waitcnt lgkmcnt(3)
	v_mfma_f32_32x32x16_bf16 v[50:65], v[66:69], v[78:81], v[50:65]
	s_waitcnt lgkmcnt(2)
	v_mfma_f32_32x32x16_bf16 v[34:49], v[70:73], v[78:81], v[34:49]
	s_waitcnt lgkmcnt(1)
	v_mfma_f32_32x32x16_bf16 v[18:33], v[74:77], v[78:81], v[18:33]
	s_waitcnt lgkmcnt(0)
	v_mfma_f32_32x32x16_bf16 v[2:17], v[82:85], v[78:81], v[2:17]
	s_setprio 1
	v_not_b32_e32 v66, v218
	v_not_b32_e32 v82, v205
	v_bfe_i32 v83, v66, 0, 1
	v_bfe_i32 v174, v82, 0, 1
	v_bfe_i32 v67, v66, 1, 1
	v_bfe_i32 v175, v82, 1, 1
	v_bfe_i32 v68, v66, 2, 1
	v_bfe_i32 v84, v82, 2, 1
	v_bfe_i32 v69, v66, 3, 1
	v_bfe_i32 v85, v82, 3, 1
	v_bfe_i32 v70, v66, 8, 1
	v_bfe_i32 v86, v82, 8, 1
	v_bfe_i32 v71, v66, 9, 1
	v_bfe_i32 v87, v82, 9, 1
	v_bfe_i32 v72, v66, 10, 1
	v_bfe_i32 v88, v82, 10, 1
	v_bfe_i32 v73, v66, 11, 1
	v_bfe_i32 v89, v82, 11, 1
	v_bfe_i32 v74, v66, 16, 1
	v_bfe_i32 v90, v82, 16, 1
	v_bfe_i32 v75, v66, 17, 1
	v_bfe_i32 v91, v82, 17, 1
	v_bfe_i32 v76, v66, 18, 1
	v_bfe_i32 v92, v82, 18, 1
	v_bfe_i32 v77, v66, 19, 1
	v_bfe_i32 v93, v82, 19, 1
	v_bfe_i32 v78, v66, 24, 1
	v_bfe_i32 v94, v82, 24, 1
	v_bfe_i32 v79, v66, 25, 1
	v_bfe_i32 v95, v82, 25, 1
	v_bfe_i32 v80, v66, 26, 1
	v_bfe_i32 v96, v82, 26, 1
	v_bfe_i32 v66, v66, 27, 1
	v_bfe_i32 v82, v82, 27, 1
	s_nop 0
	v_and_b32_e32 v79, 0xff800000, v79
	v_and_b32_e32 v81, 0xff800000, v66
	v_and_b32_e32 v66, 0xff800000, v83
	v_and_b32_e32 v97, 0xff800000, v82
	v_and_b32_e32 v83, 0xff800000, v175
	v_and_b32_e32 v82, 0xff800000, v174
	ds_read_b128 v[174:177], v217 offset:8704
	ds_read_b128 v[218:221], v217
	ds_read_b128 v[222:225], v217 offset:32
	ds_read_b128 v[226:229], v217 offset:8736
	ds_read_b128 v[232:235], v217 offset:64
	ds_read_b128 v[236:239], v217 offset:8768
	ds_read_b128 v[240:243], v217 offset:96
	ds_read_b128 v[248:251], v217 offset:8800
	v_and_b32_e32 v80, 0xff800000, v80
	v_and_b32_e32 v78, 0xff800000, v78
	v_and_b32_e32 v77, 0xff800000, v77
	v_and_b32_e32 v76, 0xff800000, v76
	v_and_b32_e32 v75, 0xff800000, v75
	v_and_b32_e32 v74, 0xff800000, v74
	v_and_b32_e32 v73, 0xff800000, v73
	v_and_b32_e32 v72, 0xff800000, v72
	v_and_b32_e32 v71, 0xff800000, v71
	v_and_b32_e32 v70, 0xff800000, v70
	v_and_b32_e32 v69, 0xff800000, v69
	v_and_b32_e32 v68, 0xff800000, v68
	v_and_b32_e32 v67, 0xff800000, v67
	v_and_b32_e32 v96, 0xff800000, v96
	v_and_b32_e32 v95, 0xff800000, v95
	v_and_b32_e32 v94, 0xff800000, v94
	v_and_b32_e32 v93, 0xff800000, v93
	v_and_b32_e32 v92, 0xff800000, v92
	v_and_b32_e32 v91, 0xff800000, v91
	v_and_b32_e32 v90, 0xff800000, v90
	v_and_b32_e32 v89, 0xff800000, v89
	v_and_b32_e32 v88, 0xff800000, v88
	v_and_b32_e32 v87, 0xff800000, v87
	v_and_b32_e32 v86, 0xff800000, v86
	v_and_b32_e32 v85, 0xff800000, v85
	v_and_b32_e32 v84, 0xff800000, v84
	s_setprio 2
	s_waitcnt lgkmcnt(6)
	v_mfma_f32_32x32x16_bf16 v[66:81], v[218:221], v[98:101], v[66:81]
	v_mfma_f32_32x32x16_bf16 v[82:97], v[174:177], v[98:101], v[82:97]
	s_waitcnt lgkmcnt(5)
	v_mfma_f32_32x32x16_bf16 v[66:81], v[222:225], v[102:105], v[66:81]
	s_waitcnt lgkmcnt(4)
	v_mfma_f32_32x32x16_bf16 v[82:97], v[226:229], v[102:105], v[82:97]
	s_waitcnt lgkmcnt(3)
	v_mfma_f32_32x32x16_bf16 v[66:81], v[232:235], v[106:109], v[66:81]
	s_waitcnt lgkmcnt(2)
	v_mfma_f32_32x32x16_bf16 v[82:97], v[236:239], v[106:109], v[82:97]
	s_waitcnt lgkmcnt(1)
	v_mfma_f32_32x32x16_bf16 v[66:81], v[240:243], v[110:113], v[66:81]
	s_waitcnt lgkmcnt(0)
	v_mfma_f32_32x32x16_bf16 v[82:97], v[248:251], v[110:113], v[82:97]
	s_setprio 1
	ds_read_b128 v[174:177], v217 offset:128
	ds_read_b128 v[218:221], v217 offset:160
	ds_read_b128 v[222:225], v217 offset:8832
	ds_read_b128 v[226:229], v217 offset:8864
	ds_read_b128 v[232:235], v217 offset:192
	ds_read_b128 v[236:239], v217 offset:224
	ds_read_b128 v[240:243], v217 offset:8896
	ds_read_b128 v[248:251], v217 offset:8928
	s_setprio 2
	s_waitcnt lgkmcnt(7)
	v_mfma_f32_32x32x16_bf16 v[66:81], v[174:177], v[114:117], v[66:81]
	s_waitcnt lgkmcnt(5)
	v_mfma_f32_32x32x16_bf16 v[82:97], v[222:225], v[114:117], v[82:97]
	v_mfma_f32_32x32x16_bf16 v[66:81], v[218:221], v[118:121], v[66:81]
	s_waitcnt lgkmcnt(4)
	v_mfma_f32_32x32x16_bf16 v[82:97], v[226:229], v[118:121], v[82:97]
	s_waitcnt lgkmcnt(3)
	v_mfma_f32_32x32x16_bf16 v[66:81], v[232:235], v[122:125], v[66:81]
	s_waitcnt lgkmcnt(1)
	v_mfma_f32_32x32x16_bf16 v[82:97], v[240:243], v[122:125], v[82:97]
	v_mfma_f32_32x32x16_bf16 v[66:81], v[236:239], v[126:129], v[66:81]
	s_waitcnt lgkmcnt(0)
	v_mfma_f32_32x32x16_bf16 v[82:97], v[248:251], v[126:129], v[82:97]
	s_setprio 1
	s_or_b64 exec, exec, s[0:1]
	s_and_b64 vcc, exec, s[8:9]
	s_cbranch_vccz .LBB0_88
	s_branch .LBB0_89

.LBB0_99:
	s_setprio 0
	s_mov_b64 s[4:5], 0
	v_readlane_b32 s33, v253, 26
